# straight-line GO merge epilogue for full-mask units (gate / ya loads ahead of the stores); on top of v043
# speedup vs baseline: 1.0073x; 1.0073x over previous
.LBB0_859:
	v_mov_b32_e32 v189, v239
	v_mov_b32_e32 v191, v241
	s_cmp_lt_i32 s85, 2
	s_mov_b64 s[0:1], -1
	s_cbranch_scc0 .LBB0_1183
	s_lshl_b32 s0, s75, 6
	s_add_i32 s0, s0, 0
	s_add_i32 s0, s0, 0x21400
	v_mov_b32_e32 v2, s0
	s_waitcnt lgkmcnt(0)
	ds_read_b96 v[134:136], v2
	v_mov_b32_e32 v2, s73
	ds_read_b32 v2, v2
	s_mov_b64 s[6:7], -1
	s_mov_b64 s[0:1], 0
	s_waitcnt lgkmcnt(0)
	v_readfirstlane_b32 s42, v134
	v_readfirstlane_b32 s36, v135
	v_readfirstlane_b32 s12, v2
	v_mov_b32_e32 v2, s77
	ds_read_b32 v2, v2
	v_readfirstlane_b32 s37, v136
	s_cmp_lt_i32 s42, 3
	s_mov_b64 s[14:15], 0
	s_waitcnt lgkmcnt(0)
	v_readfirstlane_b32 s13, v2
	s_cbranch_scc1 .LBB0_993
	s_cmp_gt_i32 s42, 3
	s_cbranch_scc0 .LBB0_966
	s_cmp_gt_i32 s42, 4
	s_cbranch_scc0 .LBB0_892
	s_cmp_eq_u32 s42, 5
	s_mov_b64 s[14:15], -1
	s_cbranch_scc0 .LBB0_891
	s_add_u32 s6, s12, 0x41900000
	s_addc_u32 s7, s13, 0
	s_add_u32 s8, s12, 0x2af00000
	s_addc_u32 s9, s13, 0
	s_cmp_eq_u32 s84, 0xff
	s_cbranch_scc1 .Lgfast
	s_lshl_b32 s10, s4, 8
	v_readlane_b32 s11, v255, 18
	s_add_i32 s10, s10, s11
	v_add_u32_e32 v162, s10, v189
	s_lshl_b32 s10, s3, 8
	s_or_b32 s10, s10, s70
	v_lshl_add_u32 v4, v191, 3, s10
	v_ashrrev_i32_e32 v5, 31, v4
	v_lshlrev_b64 v[158:159], 1, v[4:5]
	v_lshl_add_u64 v[134:135], s[12:13], 0, v[158:159]
	s_mov_b64 s[10:11], 0x3f500000
	v_lshl_add_u64 v[160:161], v[134:135], 0, s[10:11]
	v_add_u32_e32 v134, 16, v162
	s_movk_i32 s14, 0x3000
	v_ashrrev_i32_e32 v135, 31, v134
	v_mov_b64_e32 v[136:137], s[8:9]
	v_mad_i64_i32 v[138:139], s[10:11], v134, s14, v[136:137]
	v_lshlrev_b64 v[168:169], 12, v[134:135]
	v_add_u32_e32 v134, 32, v162
	v_lshl_add_u64 v[176:177], v[138:139], 0, v[158:159]
	s_movk_i32 s15, 0x2000
	v_ashrrev_i32_e32 v135, 31, v134
	v_add_co_u32_e32 v138, vcc, s15, v176
	v_lshlrev_b64 v[166:167], 12, v[134:135]
	s_nop 0
	v_addc_co_u32_e32 v139, vcc, 0, v177, vcc
	v_lshl_add_u64 v[180:181], v[160:161], 0, v[166:167]
	global_load_dwordx4 v[150:153], v[138:139], off
	global_load_dwordx4 v[146:149], v[180:181], off
	v_mad_i64_i32 v[138:139], s[10:11], v134, s14, v[136:137]
	v_lshl_add_u64 v[178:179], v[138:139], 0, v[158:159]
	v_add_co_u32_e32 v138, vcc, s15, v178
	v_lshl_add_u64 v[174:175], v[160:161], 0, v[168:169]
	s_nop 0
	v_addc_co_u32_e32 v139, vcc, 0, v179, vcc
	global_load_dwordx4 v[142:145], v[138:139], off
	v_add_u32_e32 v138, 48, v162
	v_mad_i64_i32 v[134:135], s[10:11], v138, s14, v[136:137]
	v_ashrrev_i32_e32 v139, 31, v138
	v_lshl_add_u64 v[182:183], v[134:135], 0, v[158:159]
	v_add_co_u32_e32 v134, vcc, 0x2000, v182
	v_lshlrev_b64 v[164:165], 12, v[138:139]
	s_nop 0
	v_addc_co_u32_e32 v135, vcc, 0, v183, vcc
	v_lshl_add_u64 v[184:185], v[160:161], 0, v[164:165]
	global_load_dwordx4 v[154:157], v[174:175], off
	global_load_dwordx4 v[138:141], v[184:185], off
	v_mad_i64_i32 v[172:173], s[10:11], v162, s14, 0
	global_load_dwordx4 v[134:137], v[134:135], off
	s_and_b32 s14, s84, 1
	v_ashrrev_i32_e32 v163, 31, v162
	s_bitcmp1_b32 s84, 0
	v_lshlrev_b64 v[170:171], 12, v[162:163]
	s_cselect_b64 s[10:11], -1, 0
	s_cmp_eq_u32 s14, 0
	s_cbranch_scc1 .LBB0_866
	v_lshl_add_u64 v[186:187], v[160:161], 0, v[170:171]
	global_load_dwordx4 v[204:207], v[186:187], off
	v_lshl_add_u64 v[186:187], s[8:9], 0, v[172:173]
	v_lshl_add_u64 v[186:187], v[186:187], 0, v[158:159]
	v_add_co_u32_e32 v186, vcc, 0x2000, v186
	s_nop 1
	v_addc_co_u32_e32 v187, vcc, 0, v187, vcc
	global_load_dwordx4 v[208:211], v[186:187], off
	s_waitcnt vmcnt(0)
	v_lshlrev_b32_e32 v186, 16, v204
	v_and_b32_e32 v187, 0xffff0000, v204
	v_lshlrev_b32_e32 v204, 16, v205
	v_and_b32_e32 v205, 0xffff0000, v205
	v_lshlrev_b32_e32 v212, 16, v208
	v_and_b32_e32 v213, 0xffff0000, v208
	v_lshlrev_b32_e32 v208, 16, v209
	v_and_b32_e32 v209, 0xffff0000, v209
	v_pk_fma_f32 v[208:209], v[128:129], v[208:209], v[204:205]
	v_pk_fma_f32 v[186:187], v[126:127], v[212:213], v[186:187]
	v_lshlrev_b32_e32 v204, 16, v206
	v_and_b32_e32 v205, 0xffff0000, v206
	v_lshlrev_b32_e32 v206, 16, v207
	v_and_b32_e32 v207, 0xffff0000, v207
	v_lshlrev_b32_e32 v212, 16, v210
	v_and_b32_e32 v213, 0xffff0000, v210
	v_lshlrev_b32_e32 v210, 16, v211
	v_and_b32_e32 v211, 0xffff0000, v211
	v_pk_fma_f32 v[210:211], v[132:133], v[210:211], v[206:207]
	v_pk_fma_f32 v[206:207], v[130:131], v[212:213], v[204:205]
	v_cvt_pk_bf16_f32 v204, v186, v187
	v_lshl_add_u64 v[186:187], s[6:7], 0, v[170:171]
	v_cvt_pk_bf16_f32 v205, v208, v209
	v_cvt_pk_bf16_f32 v206, v206, v207
	v_cvt_pk_bf16_f32 v207, v210, v211
	v_lshl_add_u64 v[186:187], v[186:187], 0, v[158:159]
	global_store_dwordx4 v[186:187], v[204:207], off

.Lgfast:
	s_lshl_b32 s10, s4, 8
	v_readlane_b32 s11, v255, 18
	s_add_i32 s10, s10, s11
	v_add_u32_e32 v186, s10, v189
	s_lshl_b32 s10, s3, 8
	s_or_b32 s10, s10, s70
	v_lshl_add_u32 v187, v191, 3, s10
	v_lshlrev_b32_e32 v187, 1, v187
	v_mul_u32_u24_e32 v226, 0x3000, v186
	v_add_u32_e32 v226, v226, v187
	v_lshl_add_u32 v186, v186, 12, v187
	s_add_u32 s16, s12, 0x3f500000
	s_addc_u32 s17, s13, 0
	s_add_u32 s18, s8, 0x2000
	s_addc_u32 s19, s9, 0
	global_load_dwordx4 v[204:207], v186, s[16:17]
	global_load_dwordx4 v[142:145], v226, s[18:19]
	v_add_u32_e32 v227, 0x10000, v186
	global_load_dwordx4 v[208:211], v227, s[16:17]
	v_add_u32_e32 v227, 0x30000, v226
	global_load_dwordx4 v[146:149], v227, s[18:19]
	v_add_u32_e32 v227, 0x20000, v186
	global_load_dwordx4 v[212:215], v227, s[16:17]
	v_add_u32_e32 v227, 0x60000, v226
	global_load_dwordx4 v[150:153], v227, s[18:19]
	v_add_u32_e32 v227, 0x30000, v186
	global_load_dwordx4 v[216:219], v227, s[16:17]
	v_add_u32_e32 v227, 0x90000, v226
	global_load_dwordx4 v[154:157], v227, s[18:19]
	global_load_dwordx4 v[158:161], v186, s[16:17] offset:256
	global_load_dwordx4 v[174:177], v226, s[18:19] offset:256
	v_add_u32_e32 v227, 0x10000, v186
	global_load_dwordx4 v[162:165], v227, s[16:17] offset:256
	v_add_u32_e32 v227, 0x30000, v226
	global_load_dwordx4 v[178:181], v227, s[18:19] offset:256
	v_add_u32_e32 v227, 0x20000, v186
	global_load_dwordx4 v[166:169], v227, s[16:17] offset:256
	v_add_u32_e32 v227, 0x60000, v226
	global_load_dwordx4 v[182:185], v227, s[18:19] offset:256
	v_add_u32_e32 v227, 0x30000, v186
	global_load_dwordx4 v[170:173], v227, s[16:17] offset:256
	v_add_u32_e32 v227, 0x90000, v226
	global_load_dwordx4 v[222:225], v227, s[18:19] offset:256
	s_waitcnt vmcnt(8)
	v_lshlrev_b32_e32 v134, 16, v142
	v_and_b32_e32 v135, 0xffff0000, v142
	v_lshlrev_b32_e32 v136, 16, v204
	v_and_b32_e32 v137, 0xffff0000, v204
	v_pk_fma_f32 v[126:127], v[126:127], v[134:135], v[136:137]
	v_lshlrev_b32_e32 v138, 16, v143
	v_and_b32_e32 v139, 0xffff0000, v143
	v_lshlrev_b32_e32 v140, 16, v205
	v_and_b32_e32 v141, 0xffff0000, v205
	v_pk_fma_f32 v[128:129], v[128:129], v[138:139], v[140:141]
	v_lshlrev_b32_e32 v134, 16, v144
	v_and_b32_e32 v135, 0xffff0000, v144
	v_lshlrev_b32_e32 v136, 16, v206
	v_and_b32_e32 v137, 0xffff0000, v206
	v_pk_fma_f32 v[130:131], v[130:131], v[134:135], v[136:137]
	v_lshlrev_b32_e32 v138, 16, v145
	v_and_b32_e32 v139, 0xffff0000, v145
	v_lshlrev_b32_e32 v140, 16, v207
	v_and_b32_e32 v141, 0xffff0000, v207
	v_pk_fma_f32 v[132:133], v[132:133], v[138:139], v[140:141]
	v_cvt_pk_bf16_f32 v204, v126, v127
	v_cvt_pk_bf16_f32 v205, v128, v129
	v_cvt_pk_bf16_f32 v206, v130, v131
	v_cvt_pk_bf16_f32 v207, v132, v133
	v_lshlrev_b32_e32 v134, 16, v146
	v_and_b32_e32 v135, 0xffff0000, v146
	v_lshlrev_b32_e32 v136, 16, v208
	v_and_b32_e32 v137, 0xffff0000, v208
	v_pk_fma_f32 v[118:119], v[118:119], v[134:135], v[136:137]
	v_lshlrev_b32_e32 v138, 16, v147
	v_and_b32_e32 v139, 0xffff0000, v147
	v_lshlrev_b32_e32 v140, 16, v209
	v_and_b32_e32 v141, 0xffff0000, v209
	v_pk_fma_f32 v[120:121], v[120:121], v[138:139], v[140:141]
	v_lshlrev_b32_e32 v134, 16, v148
	v_and_b32_e32 v135, 0xffff0000, v148
	v_lshlrev_b32_e32 v136, 16, v210
	v_and_b32_e32 v137, 0xffff0000, v210
	v_pk_fma_f32 v[122:123], v[122:123], v[134:135], v[136:137]
	v_lshlrev_b32_e32 v138, 16, v149
	v_and_b32_e32 v139, 0xffff0000, v149
	v_lshlrev_b32_e32 v140, 16, v211
	v_and_b32_e32 v141, 0xffff0000, v211
	v_pk_fma_f32 v[124:125], v[124:125], v[138:139], v[140:141]
	v_cvt_pk_bf16_f32 v208, v118, v119
	v_cvt_pk_bf16_f32 v209, v120, v121
	v_cvt_pk_bf16_f32 v210, v122, v123
	v_cvt_pk_bf16_f32 v211, v124, v125
	v_lshlrev_b32_e32 v134, 16, v150
	v_and_b32_e32 v135, 0xffff0000, v150
	v_lshlrev_b32_e32 v136, 16, v212
	v_and_b32_e32 v137, 0xffff0000, v212
	v_pk_fma_f32 v[110:111], v[110:111], v[134:135], v[136:137]
	v_lshlrev_b32_e32 v138, 16, v151
	v_and_b32_e32 v139, 0xffff0000, v151
	v_lshlrev_b32_e32 v140, 16, v213
	v_and_b32_e32 v141, 0xffff0000, v213
	v_pk_fma_f32 v[112:113], v[112:113], v[138:139], v[140:141]
	v_lshlrev_b32_e32 v134, 16, v152
	v_and_b32_e32 v135, 0xffff0000, v152
	v_lshlrev_b32_e32 v136, 16, v214
	v_and_b32_e32 v137, 0xffff0000, v214
	v_pk_fma_f32 v[114:115], v[114:115], v[134:135], v[136:137]
	v_lshlrev_b32_e32 v138, 16, v153
	v_and_b32_e32 v139, 0xffff0000, v153
	v_lshlrev_b32_e32 v140, 16, v215
	v_and_b32_e32 v141, 0xffff0000, v215
	v_pk_fma_f32 v[116:117], v[116:117], v[138:139], v[140:141]
	v_cvt_pk_bf16_f32 v212, v110, v111
	v_cvt_pk_bf16_f32 v213, v112, v113
	v_cvt_pk_bf16_f32 v214, v114, v115
	v_cvt_pk_bf16_f32 v215, v116, v117
	v_lshlrev_b32_e32 v134, 16, v154
	v_and_b32_e32 v135, 0xffff0000, v154
	v_lshlrev_b32_e32 v136, 16, v216
	v_and_b32_e32 v137, 0xffff0000, v216
	v_pk_fma_f32 v[102:103], v[102:103], v[134:135], v[136:137]
	v_lshlrev_b32_e32 v138, 16, v155
	v_and_b32_e32 v139, 0xffff0000, v155
	v_lshlrev_b32_e32 v140, 16, v217
	v_and_b32_e32 v141, 0xffff0000, v217
	v_pk_fma_f32 v[104:105], v[104:105], v[138:139], v[140:141]
	v_lshlrev_b32_e32 v134, 16, v156
	v_and_b32_e32 v135, 0xffff0000, v156
	v_lshlrev_b32_e32 v136, 16, v218
	v_and_b32_e32 v137, 0xffff0000, v218
	v_pk_fma_f32 v[106:107], v[106:107], v[134:135], v[136:137]
	v_lshlrev_b32_e32 v138, 16, v157
	v_and_b32_e32 v139, 0xffff0000, v157
	v_lshlrev_b32_e32 v140, 16, v219
	v_and_b32_e32 v141, 0xffff0000, v219
	v_pk_fma_f32 v[108:109], v[108:109], v[138:139], v[140:141]
	v_cvt_pk_bf16_f32 v216, v102, v103
	v_cvt_pk_bf16_f32 v217, v104, v105
	v_cvt_pk_bf16_f32 v218, v106, v107
	v_cvt_pk_bf16_f32 v219, v108, v109
	v_add_u32_e32 v227, 0x80000, v186
	global_load_dwordx4 v[102:105], v227, s[16:17]
	v_add_u32_e32 v227, 0x180000, v226
	global_load_dwordx4 v[118:121], v227, s[18:19]
	v_add_u32_e32 v227, 0x90000, v186
	global_load_dwordx4 v[106:109], v227, s[16:17]
	v_add_u32_e32 v227, 0x1b0000, v226
	global_load_dwordx4 v[122:125], v227, s[18:19]
	v_add_u32_e32 v227, 0xa0000, v186
	global_load_dwordx4 v[110:113], v227, s[16:17]
	v_add_u32_e32 v227, 0x1e0000, v226
	global_load_dwordx4 v[126:129], v227, s[18:19]
	v_add_u32_e32 v227, 0xb0000, v186
	global_load_dwordx4 v[114:117], v227, s[16:17]
	v_add_u32_e32 v227, 0x210000, v226
	global_load_dwordx4 v[130:133], v227, s[18:19]
	global_store_dwordx4 v186, v[204:207], s[6:7]
	v_add_u32_e32 v187, 0x10000, v186
	global_store_dwordx4 v187, v[208:211], s[6:7]
	v_add_u32_e32 v227, 0x20000, v186
	global_store_dwordx4 v227, v[212:215], s[6:7]
	v_add_u32_e32 v187, 0x30000, v186
	global_store_dwordx4 v187, v[216:219], s[6:7]
	s_waitcnt vmcnt(12)
	v_lshlrev_b32_e32 v134, 16, v174
	v_and_b32_e32 v135, 0xffff0000, v174
	v_lshlrev_b32_e32 v136, 16, v158
	v_and_b32_e32 v137, 0xffff0000, v158
	v_pk_fma_f32 v[94:95], v[94:95], v[134:135], v[136:137]
	v_lshlrev_b32_e32 v138, 16, v175
	v_and_b32_e32 v139, 0xffff0000, v175
	v_lshlrev_b32_e32 v140, 16, v159
	v_and_b32_e32 v141, 0xffff0000, v159
	v_pk_fma_f32 v[96:97], v[96:97], v[138:139], v[140:141]
	v_lshlrev_b32_e32 v134, 16, v176
	v_and_b32_e32 v135, 0xffff0000, v176
	v_lshlrev_b32_e32 v136, 16, v160
	v_and_b32_e32 v137, 0xffff0000, v160
	v_pk_fma_f32 v[98:99], v[98:99], v[134:135], v[136:137]
	v_lshlrev_b32_e32 v138, 16, v177
	v_and_b32_e32 v139, 0xffff0000, v177
	v_lshlrev_b32_e32 v140, 16, v161
	v_and_b32_e32 v141, 0xffff0000, v161
	v_pk_fma_f32 v[100:101], v[100:101], v[138:139], v[140:141]
	v_cvt_pk_bf16_f32 v158, v94, v95
	v_cvt_pk_bf16_f32 v159, v96, v97
	v_cvt_pk_bf16_f32 v160, v98, v99
	v_cvt_pk_bf16_f32 v161, v100, v101
	v_lshlrev_b32_e32 v134, 16, v178
	v_and_b32_e32 v135, 0xffff0000, v178
	v_lshlrev_b32_e32 v136, 16, v162
	v_and_b32_e32 v137, 0xffff0000, v162
	v_pk_fma_f32 v[86:87], v[86:87], v[134:135], v[136:137]
	v_lshlrev_b32_e32 v138, 16, v179
	v_and_b32_e32 v139, 0xffff0000, v179
	v_lshlrev_b32_e32 v140, 16, v163
	v_and_b32_e32 v141, 0xffff0000, v163
	v_pk_fma_f32 v[88:89], v[88:89], v[138:139], v[140:141]
	v_lshlrev_b32_e32 v134, 16, v180
	v_and_b32_e32 v135, 0xffff0000, v180
	v_lshlrev_b32_e32 v136, 16, v164
	v_and_b32_e32 v137, 0xffff0000, v164
	v_pk_fma_f32 v[90:91], v[90:91], v[134:135], v[136:137]
	v_lshlrev_b32_e32 v138, 16, v181
	v_and_b32_e32 v139, 0xffff0000, v181
	v_lshlrev_b32_e32 v140, 16, v165
	v_and_b32_e32 v141, 0xffff0000, v165
	v_pk_fma_f32 v[92:93], v[92:93], v[138:139], v[140:141]
	v_cvt_pk_bf16_f32 v162, v86, v87
	v_cvt_pk_bf16_f32 v163, v88, v89
	v_cvt_pk_bf16_f32 v164, v90, v91
	v_cvt_pk_bf16_f32 v165, v92, v93
	v_lshlrev_b32_e32 v134, 16, v182
	v_and_b32_e32 v135, 0xffff0000, v182
	v_lshlrev_b32_e32 v136, 16, v166
	v_and_b32_e32 v137, 0xffff0000, v166
	v_pk_fma_f32 v[78:79], v[78:79], v[134:135], v[136:137]
	v_lshlrev_b32_e32 v138, 16, v183
	v_and_b32_e32 v139, 0xffff0000, v183
	v_lshlrev_b32_e32 v140, 16, v167
	v_and_b32_e32 v141, 0xffff0000, v167
	v_pk_fma_f32 v[80:81], v[80:81], v[138:139], v[140:141]
	v_lshlrev_b32_e32 v134, 16, v184
	v_and_b32_e32 v135, 0xffff0000, v184
	v_lshlrev_b32_e32 v136, 16, v168
	v_and_b32_e32 v137, 0xffff0000, v168
	v_pk_fma_f32 v[82:83], v[82:83], v[134:135], v[136:137]
	v_lshlrev_b32_e32 v138, 16, v185
	v_and_b32_e32 v139, 0xffff0000, v185
	v_lshlrev_b32_e32 v140, 16, v169
	v_and_b32_e32 v141, 0xffff0000, v169
	v_pk_fma_f32 v[84:85], v[84:85], v[138:139], v[140:141]
	v_cvt_pk_bf16_f32 v166, v78, v79
	v_cvt_pk_bf16_f32 v167, v80, v81
	v_cvt_pk_bf16_f32 v168, v82, v83
	v_cvt_pk_bf16_f32 v169, v84, v85
	v_lshlrev_b32_e32 v134, 16, v222
	v_and_b32_e32 v135, 0xffff0000, v222
	v_lshlrev_b32_e32 v136, 16, v170
	v_and_b32_e32 v137, 0xffff0000, v170
	v_pk_fma_f32 v[70:71], v[70:71], v[134:135], v[136:137]
	v_lshlrev_b32_e32 v138, 16, v223
	v_and_b32_e32 v139, 0xffff0000, v223
	v_lshlrev_b32_e32 v140, 16, v171
	v_and_b32_e32 v141, 0xffff0000, v171
	v_pk_fma_f32 v[72:73], v[72:73], v[138:139], v[140:141]
	v_lshlrev_b32_e32 v134, 16, v224
	v_and_b32_e32 v135, 0xffff0000, v224
	v_lshlrev_b32_e32 v136, 16, v172
	v_and_b32_e32 v137, 0xffff0000, v172
	v_pk_fma_f32 v[74:75], v[74:75], v[134:135], v[136:137]
	v_lshlrev_b32_e32 v138, 16, v225
	v_and_b32_e32 v139, 0xffff0000, v225
	v_lshlrev_b32_e32 v140, 16, v173
	v_and_b32_e32 v141, 0xffff0000, v173
	v_pk_fma_f32 v[76:77], v[76:77], v[138:139], v[140:141]
	v_cvt_pk_bf16_f32 v170, v70, v71
	v_cvt_pk_bf16_f32 v171, v72, v73
	v_cvt_pk_bf16_f32 v172, v74, v75
	v_cvt_pk_bf16_f32 v173, v76, v77
	v_add_u32_e32 v227, 0x80000, v186
	global_load_dwordx4 v[70:73], v227, s[16:17] offset:256
	v_add_u32_e32 v227, 0x180000, v226
	global_load_dwordx4 v[86:89], v227, s[18:19] offset:256
	v_add_u32_e32 v227, 0x90000, v186
	global_load_dwordx4 v[74:77], v227, s[16:17] offset:256
	v_add_u32_e32 v227, 0x1b0000, v226
	global_load_dwordx4 v[90:93], v227, s[18:19] offset:256
	v_add_u32_e32 v227, 0xa0000, v186
	global_load_dwordx4 v[78:81], v227, s[16:17] offset:256
	v_add_u32_e32 v227, 0x1e0000, v226
	global_load_dwordx4 v[94:97], v227, s[18:19] offset:256
	v_add_u32_e32 v227, 0xb0000, v186
	global_load_dwordx4 v[82:85], v227, s[16:17] offset:256
	v_add_u32_e32 v227, 0x210000, v226
	global_load_dwordx4 v[98:101], v227, s[18:19] offset:256
	global_store_dwordx4 v186, v[158:161], s[6:7] offset:256
	v_add_u32_e32 v187, 0x10000, v186
	global_store_dwordx4 v187, v[162:165], s[6:7] offset:256
	v_add_u32_e32 v227, 0x20000, v186
	global_store_dwordx4 v227, v[166:169], s[6:7] offset:256
	v_add_u32_e32 v187, 0x30000, v186
	global_store_dwordx4 v187, v[170:173], s[6:7] offset:256
	s_waitcnt vmcnt(16)
	v_lshlrev_b32_e32 v134, 16, v118
	v_and_b32_e32 v135, 0xffff0000, v118
	v_lshlrev_b32_e32 v136, 16, v102
	v_and_b32_e32 v137, 0xffff0000, v102
	v_pk_fma_f32 v[46:47], v[46:47], v[134:135], v[136:137]
	v_lshlrev_b32_e32 v138, 16, v119
	v_and_b32_e32 v139, 0xffff0000, v119
	v_lshlrev_b32_e32 v140, 16, v103
	v_and_b32_e32 v141, 0xffff0000, v103
	v_pk_fma_f32 v[48:49], v[48:49], v[138:139], v[140:141]
	v_lshlrev_b32_e32 v134, 16, v120
	v_and_b32_e32 v135, 0xffff0000, v120
	v_lshlrev_b32_e32 v136, 16, v104
	v_and_b32_e32 v137, 0xffff0000, v104
	v_pk_fma_f32 v[50:51], v[50:51], v[134:135], v[136:137]
	v_lshlrev_b32_e32 v138, 16, v121
	v_and_b32_e32 v139, 0xffff0000, v121
	v_lshlrev_b32_e32 v140, 16, v105
	v_and_b32_e32 v141, 0xffff0000, v105
	v_pk_fma_f32 v[52:53], v[52:53], v[138:139], v[140:141]
	v_cvt_pk_bf16_f32 v102, v46, v47
	v_cvt_pk_bf16_f32 v103, v48, v49
	v_cvt_pk_bf16_f32 v104, v50, v51
	v_cvt_pk_bf16_f32 v105, v52, v53
	v_lshlrev_b32_e32 v134, 16, v122
	v_and_b32_e32 v135, 0xffff0000, v122
	v_lshlrev_b32_e32 v136, 16, v106
	v_and_b32_e32 v137, 0xffff0000, v106
	v_pk_fma_f32 v[38:39], v[38:39], v[134:135], v[136:137]
	v_lshlrev_b32_e32 v138, 16, v123
	v_and_b32_e32 v139, 0xffff0000, v123
	v_lshlrev_b32_e32 v140, 16, v107
	v_and_b32_e32 v141, 0xffff0000, v107
	v_pk_fma_f32 v[40:41], v[40:41], v[138:139], v[140:141]
	v_lshlrev_b32_e32 v134, 16, v124
	v_and_b32_e32 v135, 0xffff0000, v124
	v_lshlrev_b32_e32 v136, 16, v108
	v_and_b32_e32 v137, 0xffff0000, v108
	v_pk_fma_f32 v[42:43], v[42:43], v[134:135], v[136:137]
	v_lshlrev_b32_e32 v138, 16, v125
	v_and_b32_e32 v139, 0xffff0000, v125
	v_lshlrev_b32_e32 v140, 16, v109
	v_and_b32_e32 v141, 0xffff0000, v109
	v_pk_fma_f32 v[44:45], v[44:45], v[138:139], v[140:141]
	v_cvt_pk_bf16_f32 v106, v38, v39
	v_cvt_pk_bf16_f32 v107, v40, v41
	v_cvt_pk_bf16_f32 v108, v42, v43
	v_cvt_pk_bf16_f32 v109, v44, v45
	v_lshlrev_b32_e32 v134, 16, v126
	v_and_b32_e32 v135, 0xffff0000, v126
	v_lshlrev_b32_e32 v136, 16, v110
	v_and_b32_e32 v137, 0xffff0000, v110
	v_pk_fma_f32 v[30:31], v[30:31], v[134:135], v[136:137]
	v_lshlrev_b32_e32 v138, 16, v127
	v_and_b32_e32 v139, 0xffff0000, v127
	v_lshlrev_b32_e32 v140, 16, v111
	v_and_b32_e32 v141, 0xffff0000, v111
	v_pk_fma_f32 v[32:33], v[32:33], v[138:139], v[140:141]
	v_lshlrev_b32_e32 v134, 16, v128
	v_and_b32_e32 v135, 0xffff0000, v128
	v_lshlrev_b32_e32 v136, 16, v112
	v_and_b32_e32 v137, 0xffff0000, v112
	v_pk_fma_f32 v[34:35], v[34:35], v[134:135], v[136:137]
	v_lshlrev_b32_e32 v138, 16, v129
	v_and_b32_e32 v139, 0xffff0000, v129
	v_lshlrev_b32_e32 v140, 16, v113
	v_and_b32_e32 v141, 0xffff0000, v113
	v_pk_fma_f32 v[36:37], v[36:37], v[138:139], v[140:141]
	v_cvt_pk_bf16_f32 v110, v30, v31
	v_cvt_pk_bf16_f32 v111, v32, v33
	v_cvt_pk_bf16_f32 v112, v34, v35
	v_cvt_pk_bf16_f32 v113, v36, v37
	v_lshlrev_b32_e32 v134, 16, v130
	v_and_b32_e32 v135, 0xffff0000, v130
	v_lshlrev_b32_e32 v136, 16, v114
	v_and_b32_e32 v137, 0xffff0000, v114
	v_pk_fma_f32 v[22:23], v[22:23], v[134:135], v[136:137]
	v_lshlrev_b32_e32 v138, 16, v131
	v_and_b32_e32 v139, 0xffff0000, v131
	v_lshlrev_b32_e32 v140, 16, v115
	v_and_b32_e32 v141, 0xffff0000, v115
	v_pk_fma_f32 v[24:25], v[24:25], v[138:139], v[140:141]
	v_lshlrev_b32_e32 v134, 16, v132
	v_and_b32_e32 v135, 0xffff0000, v132
	v_lshlrev_b32_e32 v136, 16, v116
	v_and_b32_e32 v137, 0xffff0000, v116
	v_pk_fma_f32 v[26:27], v[26:27], v[134:135], v[136:137]
	v_lshlrev_b32_e32 v138, 16, v133
	v_and_b32_e32 v139, 0xffff0000, v133
	v_lshlrev_b32_e32 v140, 16, v117
	v_and_b32_e32 v141, 0xffff0000, v117
	v_pk_fma_f32 v[28:29], v[28:29], v[138:139], v[140:141]
	v_cvt_pk_bf16_f32 v114, v22, v23
	v_cvt_pk_bf16_f32 v115, v24, v25
	v_cvt_pk_bf16_f32 v116, v26, v27
	v_cvt_pk_bf16_f32 v117, v28, v29
	v_add_u32_e32 v227, 0x80000, v186
	global_store_dwordx4 v227, v[102:105], s[6:7]
	v_add_u32_e32 v187, 0x90000, v186
	global_store_dwordx4 v187, v[106:109], s[6:7]
	v_add_u32_e32 v227, 0xa0000, v186
	global_store_dwordx4 v227, v[110:113], s[6:7]
	v_add_u32_e32 v187, 0xb0000, v186
	global_store_dwordx4 v187, v[114:117], s[6:7]
	s_waitcnt vmcnt(8)
	v_lshlrev_b32_e32 v134, 16, v86
	v_and_b32_e32 v135, 0xffff0000, v86
	v_lshlrev_b32_e32 v136, 16, v70
	v_and_b32_e32 v137, 0xffff0000, v70
	v_pk_fma_f32 v[14:15], v[14:15], v[134:135], v[136:137]
	v_lshlrev_b32_e32 v138, 16, v87
	v_and_b32_e32 v139, 0xffff0000, v87
	v_lshlrev_b32_e32 v140, 16, v71
	v_and_b32_e32 v141, 0xffff0000, v71
	v_pk_fma_f32 v[16:17], v[16:17], v[138:139], v[140:141]
	v_lshlrev_b32_e32 v134, 16, v88
	v_and_b32_e32 v135, 0xffff0000, v88
	v_lshlrev_b32_e32 v136, 16, v72
	v_and_b32_e32 v137, 0xffff0000, v72
	v_pk_fma_f32 v[18:19], v[18:19], v[134:135], v[136:137]
	v_lshlrev_b32_e32 v138, 16, v89
	v_and_b32_e32 v139, 0xffff0000, v89
	v_lshlrev_b32_e32 v140, 16, v73
	v_and_b32_e32 v141, 0xffff0000, v73
	v_pk_fma_f32 v[20:21], v[20:21], v[138:139], v[140:141]
	v_cvt_pk_bf16_f32 v70, v14, v15
	v_cvt_pk_bf16_f32 v71, v16, v17
	v_cvt_pk_bf16_f32 v72, v18, v19
	v_cvt_pk_bf16_f32 v73, v20, v21
	v_lshlrev_b32_e32 v134, 16, v90
	v_and_b32_e32 v135, 0xffff0000, v90
	v_lshlrev_b32_e32 v136, 16, v74
	v_and_b32_e32 v137, 0xffff0000, v74
	v_pk_fma_f32 v[6:7], v[6:7], v[134:135], v[136:137]
	v_lshlrev_b32_e32 v138, 16, v91
	v_and_b32_e32 v139, 0xffff0000, v91
	v_lshlrev_b32_e32 v140, 16, v75
	v_and_b32_e32 v141, 0xffff0000, v75
	v_pk_fma_f32 v[8:9], v[8:9], v[138:139], v[140:141]
	v_lshlrev_b32_e32 v134, 16, v92
	v_and_b32_e32 v135, 0xffff0000, v92
	v_lshlrev_b32_e32 v136, 16, v76
	v_and_b32_e32 v137, 0xffff0000, v76
	v_pk_fma_f32 v[10:11], v[10:11], v[134:135], v[136:137]
	v_lshlrev_b32_e32 v138, 16, v93
	v_and_b32_e32 v139, 0xffff0000, v93
	v_lshlrev_b32_e32 v140, 16, v77
	v_and_b32_e32 v141, 0xffff0000, v77
	v_pk_fma_f32 v[12:13], v[12:13], v[138:139], v[140:141]
	v_cvt_pk_bf16_f32 v74, v6, v7
	v_cvt_pk_bf16_f32 v75, v8, v9
	v_cvt_pk_bf16_f32 v76, v10, v11
	v_cvt_pk_bf16_f32 v77, v12, v13
	v_lshlrev_b32_e32 v134, 16, v94
	v_and_b32_e32 v135, 0xffff0000, v94
	v_lshlrev_b32_e32 v136, 16, v78
	v_and_b32_e32 v137, 0xffff0000, v78
	v_pk_fma_f32 v[54:55], v[54:55], v[134:135], v[136:137]
	v_lshlrev_b32_e32 v138, 16, v95
	v_and_b32_e32 v139, 0xffff0000, v95
	v_lshlrev_b32_e32 v140, 16, v79
	v_and_b32_e32 v141, 0xffff0000, v79
	v_pk_fma_f32 v[56:57], v[56:57], v[138:139], v[140:141]
	v_lshlrev_b32_e32 v134, 16, v96
	v_and_b32_e32 v135, 0xffff0000, v96
	v_lshlrev_b32_e32 v136, 16, v80
	v_and_b32_e32 v137, 0xffff0000, v80
	v_pk_fma_f32 v[62:63], v[62:63], v[134:135], v[136:137]
	v_lshlrev_b32_e32 v138, 16, v97
	v_and_b32_e32 v139, 0xffff0000, v97
	v_lshlrev_b32_e32 v140, 16, v81
	v_and_b32_e32 v141, 0xffff0000, v81
	v_pk_fma_f32 v[64:65], v[64:65], v[138:139], v[140:141]
	v_cvt_pk_bf16_f32 v78, v54, v55
	v_cvt_pk_bf16_f32 v79, v56, v57
	v_cvt_pk_bf16_f32 v80, v62, v63
	v_cvt_pk_bf16_f32 v81, v64, v65
	v_lshlrev_b32_e32 v134, 16, v98
	v_and_b32_e32 v135, 0xffff0000, v98
	v_lshlrev_b32_e32 v136, 16, v82
	v_and_b32_e32 v137, 0xffff0000, v82
	v_pk_fma_f32 v[58:59], v[58:59], v[134:135], v[136:137]
	v_lshlrev_b32_e32 v138, 16, v99
	v_and_b32_e32 v139, 0xffff0000, v99
	v_lshlrev_b32_e32 v140, 16, v83
	v_and_b32_e32 v141, 0xffff0000, v83
	v_pk_fma_f32 v[60:61], v[60:61], v[138:139], v[140:141]
	v_lshlrev_b32_e32 v134, 16, v100
	v_and_b32_e32 v135, 0xffff0000, v100
	v_lshlrev_b32_e32 v136, 16, v84
	v_and_b32_e32 v137, 0xffff0000, v84
	v_pk_fma_f32 v[66:67], v[66:67], v[134:135], v[136:137]
	v_lshlrev_b32_e32 v138, 16, v101
	v_and_b32_e32 v139, 0xffff0000, v101
	v_lshlrev_b32_e32 v140, 16, v85
	v_and_b32_e32 v141, 0xffff0000, v85
	v_pk_fma_f32 v[68:69], v[68:69], v[138:139], v[140:141]
	v_cvt_pk_bf16_f32 v82, v58, v59
	v_cvt_pk_bf16_f32 v83, v60, v61
	v_cvt_pk_bf16_f32 v84, v66, v67
	v_cvt_pk_bf16_f32 v85, v68, v69
	v_add_u32_e32 v227, 0x80000, v186
	global_store_dwordx4 v227, v[70:73], s[6:7] offset:256
	v_add_u32_e32 v187, 0x90000, v186
	global_store_dwordx4 v187, v[74:77], s[6:7] offset:256
	v_add_u32_e32 v227, 0xa0000, v186
	global_store_dwordx4 v227, v[78:81], s[6:7] offset:256
	v_add_u32_e32 v187, 0xb0000, v186
	global_store_dwordx4 v187, v[82:85], s[6:7] offset:256
	s_branch .LBB0_890
